# P14c: P16 + next_unit producer on wave 4 with the re-stagger barrier behind next_unit; K-loop byte phases matched to P16
# baseline (speedup 1.0000x reference)
; __device__ __forceinline__ void gemm_phase(LAS unsigned char* lds, const Call& C, const int tid, const Args& args) {
;     ...
;         next_unit(C, ui + 1, nxt.pm, nxt.pn, nxt.kp0, nxt.np, nxt.slice);
;         const bool has_next = nxt.pm >= 0;
;         const char* nA = has_next ? PG8_APTR(nxt) : cA; const char* nB = has_next ? PG8_BPTR(nxt) : cB;
;         const int nt = 2 * cur.np;
.LBB0_282:
	s_cmp_lg_u32 s24, 2
	s_cbranch_scc1 .Lnu_nofetch
	s_cmp_eq_u32 s20, 0x1000
	s_cbranch_scc1 .Lnu_nofetch
	s_and_b32 vcc_lo, s92, 1
	s_lshl_b32 vcc_lo, vcc_lo, 6
	s_add_i32 vcc_lo, vcc_lo, 0x20200
	v_mov_b32_e32 v212, vcc_lo
	ds_read_b128 v[200:203], v212
	ds_read_b128 v[206:209], v212 offset:16
	ds_read_b64 v[210:211], v212 offset:32
	s_waitcnt lgkmcnt(0)
	v_readfirstlane_b32 s91, v200
	v_readfirstlane_b32 s54, v201
	v_readfirstlane_b32 s95, v202
	v_readfirstlane_b32 s5, v203
	v_readfirstlane_b32 s48, v206
	v_readfirstlane_b32 s49, v207
	v_readfirstlane_b32 s86, v208
	v_readfirstlane_b32 s87, v209
	v_readfirstlane_b32 s36, v210
	v_readfirstlane_b32 s37, v211
	s_nop 3
	s_nop 0
